# P4: ALIGN_EPI off (leading half's epilogue overlaps trailing half's last MFMA block)
# baseline (speedup 1.0000x reference)
.LBB0_808:
	ds_read_b128 v[144:147], v152
	ds_read_b128 v[156:159], v152 offset:1024
	ds_read_b128 v[160:163], v152 offset:2048
	ds_read_b128 v[164:167], v152 offset:3072
	ds_read_b128 v[168:171], v153
	ds_read_b128 v[172:175], v153 offset:1024
	ds_read_b128 v[176:179], v153 offset:2048
	ds_read_b128 v[180:183], v153 offset:3072
	s_add_u32 s34, s30, 0xfff80080
	s_addc_u32 s35, s31, -1
	s_cmp_eq_u32 s55, 28
	s_cselect_b32 s37, s19, s35
	s_cselect_b32 s36, s51, s34
	s_cselect_b32 s35, s17, s54
	s_cselect_b32 s34, s52, s53
	v_lshl_add_u64 v[148:149], s[30:31], 0, v[138:139]
	s_add_i32 m0, s27, 0xc000
	ds_read_b128 v[184:187], v154
	ds_read_b128 v[188:191], v154 offset:1024
	ds_read_b128 v[196:199], v154 offset:2048
	ds_read_b128 v[200:203], v154 offset:3072
	ds_read_b128 v[204:207], v154 offset:4096
	ds_read_b128 v[208:211], v154 offset:5120
	ds_read_b128 v[212:215], v154 offset:6144
	ds_read_b128 v[216:219], v154 offset:7168
	global_load_lds_dwordx4 v[148:149], off
	v_lshl_add_u64 v[148:149], s[30:31], 0, v[140:141]
	s_add_i32 m0, s27, 0xe000
	s_nop 0
	global_load_lds_dwordx4 v[148:149], off
	s_waitcnt vmcnt(8)
	s_waitcnt lgkmcnt(0)
	s_barrier
	v_mfma_f32_16x16x32_bf16 v[126:129], v[144:147], v[184:187], v[126:129]
	v_mfma_f32_16x16x32_bf16 v[122:125], v[160:163], v[184:187], v[122:125]
	v_mfma_f32_16x16x32_bf16 v[110:113], v[144:147], v[196:199], v[110:113]
	v_mfma_f32_16x16x32_bf16 v[106:109], v[160:163], v[196:199], v[106:109]
	v_mfma_f32_16x16x32_bf16 v[94:97], v[144:147], v[204:207], v[94:97]
	v_mfma_f32_16x16x32_bf16 v[90:93], v[160:163], v[204:207], v[90:93]
	v_mfma_f32_16x16x32_bf16 v[78:81], v[144:147], v[212:215], v[78:81]
	v_mfma_f32_16x16x32_bf16 v[74:77], v[160:163], v[212:215], v[74:77]
	v_mfma_f32_16x16x32_bf16 v[126:129], v[156:159], v[188:191], v[126:129]
	v_mfma_f32_16x16x32_bf16 v[122:125], v[164:167], v[188:191], v[122:125]
	v_mfma_f32_16x16x32_bf16 v[110:113], v[156:159], v[200:203], v[110:113]
	v_mfma_f32_16x16x32_bf16 v[106:109], v[164:167], v[200:203], v[106:109]
	v_mfma_f32_16x16x32_bf16 v[94:97], v[156:159], v[208:211], v[94:97]
	v_mfma_f32_16x16x32_bf16 v[90:93], v[164:167], v[208:211], v[90:93]
	v_mfma_f32_16x16x32_bf16 v[78:81], v[156:159], v[216:219], v[78:81]
	v_mfma_f32_16x16x32_bf16 v[74:77], v[164:167], v[216:219], v[74:77]
	v_mfma_f32_16x16x32_bf16 v[118:121], v[168:171], v[184:187], v[118:121]
	v_mfma_f32_16x16x32_bf16 v[114:117], v[176:179], v[184:187], v[114:117]
	v_mfma_f32_16x16x32_bf16 v[102:105], v[168:171], v[196:199], v[102:105]
	v_mfma_f32_16x16x32_bf16 v[98:101], v[176:179], v[196:199], v[98:101]
	v_mfma_f32_16x16x32_bf16 v[86:89], v[168:171], v[204:207], v[86:89]
	v_mfma_f32_16x16x32_bf16 v[82:85], v[176:179], v[204:207], v[82:85]
	v_mfma_f32_16x16x32_bf16 v[70:73], v[168:171], v[212:215], v[70:73]
	v_mfma_f32_16x16x32_bf16 v[66:69], v[176:179], v[212:215], v[66:69]
	v_mfma_f32_16x16x32_bf16 v[118:121], v[172:175], v[188:191], v[118:121]
	v_mfma_f32_16x16x32_bf16 v[114:117], v[180:183], v[188:191], v[114:117]
	v_mfma_f32_16x16x32_bf16 v[102:105], v[172:175], v[200:203], v[102:105]
	v_mfma_f32_16x16x32_bf16 v[98:101], v[180:183], v[200:203], v[98:101]
	v_mfma_f32_16x16x32_bf16 v[86:89], v[172:175], v[208:211], v[86:89]
	v_mfma_f32_16x16x32_bf16 v[82:85], v[180:183], v[208:211], v[82:85]
	v_mfma_f32_16x16x32_bf16 v[70:73], v[172:175], v[216:219], v[70:73]
	v_mfma_f32_16x16x32_bf16 v[66:69], v[180:183], v[216:219], v[66:69]
	s_barrier
	s_add_i32 s56, s47, s38
	v_lshl_add_u64 v[148:149], s[34:35], 0, v[132:133]
	s_mov_b32 m0, s56
	ds_read_b128 v[184:187], v154 offset:16384
	ds_read_b128 v[188:191], v154 offset:17408
	ds_read_b128 v[196:199], v154 offset:18432
	ds_read_b128 v[200:203], v154 offset:19456
	ds_read_b128 v[204:207], v154 offset:20480
	ds_read_b128 v[208:211], v154 offset:21504
	ds_read_b128 v[212:215], v154 offset:22528
	ds_read_b128 v[216:219], v154 offset:23552
	global_load_lds_dwordx4 v[148:149], off
	s_add_i32 m0, s56, 0x2000
	s_add_u32 s56, s34, 0x80000
	v_lshl_add_u64 v[192:193], s[34:35], 0, v[136:137]
	s_addc_u32 s57, s35, 0
	s_add_i32 s58, s48, s38
	global_load_lds_dwordx4 v[192:193], off
	v_lshl_add_u64 v[220:221], s[56:57], 0, v[132:133]
	s_mov_b32 m0, s58
	v_lshl_add_u64 v[222:223], s[36:37], 0, v[134:135]
	global_load_lds_dwordx4 v[220:221], off
	v_lshl_add_u64 v[220:221], s[56:57], 0, v[136:137]
	s_add_i32 m0, s58, 0x2000
	s_nop 0
	global_load_lds_dwordx4 v[220:221], off
	v_lshl_add_u64 v[220:221], s[36:37], 0, v[130:131]
	s_mov_b32 m0, s27
	s_nop 0
	global_load_lds_dwordx4 v[220:221], off
	s_mov_b32 m0, s29
	s_nop 0
	global_load_lds_dwordx4 v[222:223], off
	s_waitcnt vmcnt(8)
	s_waitcnt lgkmcnt(0)
	s_barrier
	v_mfma_f32_16x16x32_bf16 v[62:65], v[144:147], v[184:187], v[62:65]
	v_mfma_f32_16x16x32_bf16 v[58:61], v[160:163], v[184:187], v[58:61]
	v_mfma_f32_16x16x32_bf16 v[46:49], v[144:147], v[196:199], v[46:49]
	v_mfma_f32_16x16x32_bf16 v[42:45], v[160:163], v[196:199], v[42:45]
	v_mfma_f32_16x16x32_bf16 v[30:33], v[144:147], v[204:207], v[30:33]
	v_mfma_f32_16x16x32_bf16 v[26:29], v[160:163], v[204:207], v[26:29]
	v_mfma_f32_16x16x32_bf16 v[14:17], v[144:147], v[212:215], v[14:17]
	v_mfma_f32_16x16x32_bf16 v[10:13], v[160:163], v[212:215], v[10:13]
	v_mfma_f32_16x16x32_bf16 v[62:65], v[156:159], v[188:191], v[62:65]
	v_mfma_f32_16x16x32_bf16 v[58:61], v[164:167], v[188:191], v[58:61]
	v_mfma_f32_16x16x32_bf16 v[46:49], v[156:159], v[200:203], v[46:49]
	v_mfma_f32_16x16x32_bf16 v[42:45], v[164:167], v[200:203], v[42:45]
	v_mfma_f32_16x16x32_bf16 v[30:33], v[156:159], v[208:211], v[30:33]
	v_mfma_f32_16x16x32_bf16 v[26:29], v[164:167], v[208:211], v[26:29]
	v_mfma_f32_16x16x32_bf16 v[14:17], v[156:159], v[216:219], v[14:17]
	v_mfma_f32_16x16x32_bf16 v[10:13], v[164:167], v[216:219], v[10:13]
	v_mfma_f32_16x16x32_bf16 v[54:57], v[168:171], v[184:187], v[54:57]
	v_mfma_f32_16x16x32_bf16 v[50:53], v[176:179], v[184:187], v[50:53]
	v_mfma_f32_16x16x32_bf16 v[38:41], v[168:171], v[196:199], v[38:41]
	v_mfma_f32_16x16x32_bf16 v[34:37], v[176:179], v[196:199], v[34:37]
	v_mfma_f32_16x16x32_bf16 v[22:25], v[168:171], v[204:207], v[22:25]
	v_mfma_f32_16x16x32_bf16 v[18:21], v[176:179], v[204:207], v[18:21]
	v_mfma_f32_16x16x32_bf16 v[6:9], v[168:171], v[212:215], v[6:9]
	v_mfma_f32_16x16x32_bf16 v[2:5], v[176:179], v[212:215], v[2:5]
	v_mfma_f32_16x16x32_bf16 v[54:57], v[172:175], v[188:191], v[54:57]
	v_mfma_f32_16x16x32_bf16 v[50:53], v[180:183], v[188:191], v[50:53]
	v_mfma_f32_16x16x32_bf16 v[38:41], v[172:175], v[200:203], v[38:41]
	v_mfma_f32_16x16x32_bf16 v[34:37], v[180:183], v[200:203], v[34:37]
	v_mfma_f32_16x16x32_bf16 v[22:25], v[172:175], v[208:211], v[22:25]
	v_mfma_f32_16x16x32_bf16 v[18:21], v[180:183], v[208:211], v[18:21]
	v_mfma_f32_16x16x32_bf16 v[6:9], v[172:175], v[216:219], v[6:9]
	v_mfma_f32_16x16x32_bf16 v[2:5], v[180:183], v[216:219], v[2:5]
	s_barrier
	s_add_i32 s56, 0, 0x18000
	v_add_u32_e32 v155, s56, v150
	s_add_i32 s57, 0, 0x1c000
	ds_read_b128 v[144:147], v155
	ds_read_b128 v[156:159], v155 offset:1024
	ds_read_b128 v[160:163], v155 offset:2048
	ds_read_b128 v[164:167], v155 offset:3072
	v_add_u32_e32 v155, s57, v150
	ds_read_b128 v[168:171], v155
	ds_read_b128 v[172:175], v155 offset:1024
	ds_read_b128 v[176:179], v155 offset:2048
	ds_read_b128 v[180:183], v155 offset:3072
	s_add_u32 s36, s36, 0x80000
	s_addc_u32 s37, s37, 0
	s_mov_b32 m0, s39
	v_lshl_add_u64 v[224:225], s[36:37], 0, v[130:131]
	ds_read_b128 v[184:187], v154 offset:32768
	ds_read_b128 v[188:191], v154 offset:33792
	ds_read_b128 v[196:199], v154 offset:34816
	ds_read_b128 v[200:203], v154 offset:35840
	ds_read_b128 v[204:207], v154 offset:36864
	ds_read_b128 v[208:211], v154 offset:37888
	ds_read_b128 v[212:215], v154 offset:38912
	ds_read_b128 v[216:219], v154 offset:39936
	global_load_lds_dwordx4 v[224:225], off
	v_lshl_add_u64 v[224:225], s[36:37], 0, v[134:135]
	s_mov_b32 m0, s40
	s_nop 0
	global_load_lds_dwordx4 v[224:225], off
	s_waitcnt vmcnt(8)
	s_waitcnt lgkmcnt(0)
	s_barrier
	v_mfma_f32_16x16x32_bf16 v[126:129], v[144:147], v[184:187], v[126:129]
	v_mfma_f32_16x16x32_bf16 v[122:125], v[160:163], v[184:187], v[122:125]
	v_mfma_f32_16x16x32_bf16 v[110:113], v[144:147], v[196:199], v[110:113]
	v_mfma_f32_16x16x32_bf16 v[106:109], v[160:163], v[196:199], v[106:109]
	v_mfma_f32_16x16x32_bf16 v[94:97], v[144:147], v[204:207], v[94:97]
	v_mfma_f32_16x16x32_bf16 v[90:93], v[160:163], v[204:207], v[90:93]
	v_mfma_f32_16x16x32_bf16 v[78:81], v[144:147], v[212:215], v[78:81]
	v_mfma_f32_16x16x32_bf16 v[74:77], v[160:163], v[212:215], v[74:77]
	v_mfma_f32_16x16x32_bf16 v[126:129], v[156:159], v[188:191], v[126:129]
	v_mfma_f32_16x16x32_bf16 v[122:125], v[164:167], v[188:191], v[122:125]
	v_mfma_f32_16x16x32_bf16 v[110:113], v[156:159], v[200:203], v[110:113]
	v_mfma_f32_16x16x32_bf16 v[106:109], v[164:167], v[200:203], v[106:109]
	v_mfma_f32_16x16x32_bf16 v[94:97], v[156:159], v[208:211], v[94:97]
	v_mfma_f32_16x16x32_bf16 v[90:93], v[164:167], v[208:211], v[90:93]
	v_mfma_f32_16x16x32_bf16 v[78:81], v[156:159], v[216:219], v[78:81]
	v_mfma_f32_16x16x32_bf16 v[74:77], v[164:167], v[216:219], v[74:77]
	v_mfma_f32_16x16x32_bf16 v[118:121], v[168:171], v[184:187], v[118:121]
	v_mfma_f32_16x16x32_bf16 v[114:117], v[176:179], v[184:187], v[114:117]
	v_mfma_f32_16x16x32_bf16 v[102:105], v[168:171], v[196:199], v[102:105]
	v_mfma_f32_16x16x32_bf16 v[98:101], v[176:179], v[196:199], v[98:101]
	v_mfma_f32_16x16x32_bf16 v[86:89], v[168:171], v[204:207], v[86:89]
	v_mfma_f32_16x16x32_bf16 v[82:85], v[176:179], v[204:207], v[82:85]
	v_mfma_f32_16x16x32_bf16 v[70:73], v[168:171], v[212:215], v[70:73]
	v_mfma_f32_16x16x32_bf16 v[66:69], v[176:179], v[212:215], v[66:69]
	v_mfma_f32_16x16x32_bf16 v[118:121], v[172:175], v[188:191], v[118:121]
	v_mfma_f32_16x16x32_bf16 v[114:117], v[180:183], v[188:191], v[114:117]
	v_mfma_f32_16x16x32_bf16 v[102:105], v[172:175], v[200:203], v[102:105]
	v_mfma_f32_16x16x32_bf16 v[98:101], v[180:183], v[200:203], v[98:101]
	v_mfma_f32_16x16x32_bf16 v[86:89], v[172:175], v[208:211], v[86:89]
	v_mfma_f32_16x16x32_bf16 v[82:85], v[180:183], v[208:211], v[82:85]
	v_mfma_f32_16x16x32_bf16 v[70:73], v[172:175], v[216:219], v[70:73]
	v_mfma_f32_16x16x32_bf16 v[66:69], v[180:183], v[216:219], v[66:69]
	s_barrier
;     __device__ __forceinline__ void operator()(const f32x4 (&acc)[2][2][4][2], const Unit& u, int wr, int wc, int fr, int fq) const {
;     ...
;         if (need && u.pn < 8) { unsigned sp = 0u; while (__hip_atomic_load(guard, __ATOMIC_RELAXED, __HIP_MEMORY_SCOPE_AGENT) < need && ++sp < (1u << 22)) __builtin_amdgcn_s_sleep(2); }
	s_add_i32 s36, s56, s38
	v_lshl_add_u64 v[148:149], v[148:149], 0, s[10:11]
	s_mov_b32 m0, s36
	ds_read_b128 v[184:187], v154 offset:49152
	ds_read_b128 v[188:191], v154 offset:50176
	ds_read_b128 v[196:199], v154 offset:51200
	ds_read_b128 v[200:203], v154 offset:52224
	ds_read_b128 v[204:207], v154 offset:53248
	ds_read_b128 v[208:211], v154 offset:54272
	ds_read_b128 v[212:215], v154 offset:55296
	ds_read_b128 v[216:219], v154 offset:56320
	global_load_lds_dwordx4 v[148:149], off
	s_add_i32 m0, s36, 0x2000
	s_add_u32 s34, s34, 0x80080
	v_lshl_add_u64 v[148:149], v[192:193], 0, s[10:11]
	s_addc_u32 s35, s35, 0
	s_add_i32 s36, s57, s38
	global_load_lds_dwordx4 v[148:149], off
	v_lshl_add_u64 v[148:149], s[34:35], 0, v[132:133]
	s_mov_b32 m0, s36
	s_nop 0
	global_load_lds_dwordx4 v[148:149], off
	v_lshl_add_u64 v[148:149], s[34:35], 0, v[136:137]
	s_add_i32 m0, s36, 0x2000
	s_nop 0
	global_load_lds_dwordx4 v[148:149], off
	v_lshl_add_u64 v[148:149], v[220:221], 0, s[10:11]
	s_mov_b32 m0, s42
	s_nop 0
	global_load_lds_dwordx4 v[148:149], off
	v_lshl_add_u64 v[148:149], v[222:223], 0, s[10:11]
	s_mov_b32 m0, s43
	s_nop 0
	global_load_lds_dwordx4 v[148:149], off
	s_waitcnt vmcnt(8)
	s_waitcnt lgkmcnt(0)
	s_barrier
	v_mfma_f32_16x16x32_bf16 v[62:65], v[144:147], v[184:187], v[62:65]
	v_mfma_f32_16x16x32_bf16 v[58:61], v[160:163], v[184:187], v[58:61]
	v_mfma_f32_16x16x32_bf16 v[46:49], v[144:147], v[196:199], v[46:49]
	v_mfma_f32_16x16x32_bf16 v[42:45], v[160:163], v[196:199], v[42:45]
	v_mfma_f32_16x16x32_bf16 v[30:33], v[144:147], v[204:207], v[30:33]
	v_mfma_f32_16x16x32_bf16 v[26:29], v[160:163], v[204:207], v[26:29]
	v_mfma_f32_16x16x32_bf16 v[14:17], v[144:147], v[212:215], v[14:17]
	v_mfma_f32_16x16x32_bf16 v[10:13], v[160:163], v[212:215], v[10:13]
	v_mfma_f32_16x16x32_bf16 v[62:65], v[156:159], v[188:191], v[62:65]
	v_mfma_f32_16x16x32_bf16 v[58:61], v[164:167], v[188:191], v[58:61]
	v_mfma_f32_16x16x32_bf16 v[46:49], v[156:159], v[200:203], v[46:49]
	v_mfma_f32_16x16x32_bf16 v[42:45], v[164:167], v[200:203], v[42:45]
	v_mfma_f32_16x16x32_bf16 v[30:33], v[156:159], v[208:211], v[30:33]
	v_mfma_f32_16x16x32_bf16 v[26:29], v[164:167], v[208:211], v[26:29]
	v_mfma_f32_16x16x32_bf16 v[14:17], v[156:159], v[216:219], v[14:17]
	v_mfma_f32_16x16x32_bf16 v[10:13], v[164:167], v[216:219], v[10:13]
	v_mfma_f32_16x16x32_bf16 v[54:57], v[168:171], v[184:187], v[54:57]
	v_mfma_f32_16x16x32_bf16 v[50:53], v[176:179], v[184:187], v[50:53]
	v_mfma_f32_16x16x32_bf16 v[38:41], v[168:171], v[196:199], v[38:41]
	v_mfma_f32_16x16x32_bf16 v[34:37], v[176:179], v[196:199], v[34:37]
	v_mfma_f32_16x16x32_bf16 v[22:25], v[168:171], v[204:207], v[22:25]
	v_mfma_f32_16x16x32_bf16 v[18:21], v[176:179], v[204:207], v[18:21]
	v_mfma_f32_16x16x32_bf16 v[6:9], v[168:171], v[212:215], v[6:9]
	v_mfma_f32_16x16x32_bf16 v[2:5], v[176:179], v[212:215], v[2:5]
	v_mfma_f32_16x16x32_bf16 v[54:57], v[172:175], v[188:191], v[54:57]
	v_mfma_f32_16x16x32_bf16 v[50:53], v[180:183], v[188:191], v[50:53]
	v_mfma_f32_16x16x32_bf16 v[38:41], v[172:175], v[200:203], v[38:41]
	v_mfma_f32_16x16x32_bf16 v[34:37], v[180:183], v[200:203], v[34:37]
	v_mfma_f32_16x16x32_bf16 v[22:25], v[172:175], v[208:211], v[22:25]
	v_mfma_f32_16x16x32_bf16 v[18:21], v[180:183], v[208:211], v[18:21]
	v_mfma_f32_16x16x32_bf16 v[6:9], v[172:175], v[216:219], v[6:9]
	v_mfma_f32_16x16x32_bf16 v[2:5], v[180:183], v[216:219], v[2:5]
	s_barrier
	s_add_i32 s55, s55, 2
	s_add_u32 s53, s53, 0x100
	s_addc_u32 s54, s54, 0
	s_add_u32 s30, s30, 0x100
	s_addc_u32 s31, s31, 0
	s_cmp_gt_u32 s55, 29
	s_cbranch_scc0 .LBB0_808
	s_and_b64 vcc, exec, s[12:13]
	s_cbranch_vccz .LBB0_811
.LBB0_811:
	s_cmp_lt_i32 s28, 8
	s_cselect_b64 s[30:31], -1, 0
	s_and_b64 s[30:31], s[62:63], s[30:31]
	s_andn2_b64 vcc, exec, s[30:31]
	s_cbranch_vccnz .LBB0_823
	global_load_dword v144, v133, s[4:5] sc1
	s_waitcnt vmcnt(0)
	v_cmp_lt_u32_e32 vcc, s49, v144
	s_cbranch_vccnz .LBB0_823
	s_mov_b32 s17, 0x3ffff8
	s_branch .LBB0_815

; __device__ __forceinline__ unsigned cvt_pk_bf16(float lo, float hi) { unsigned r; asm volatile("v_cvt_pk_bf16_f32 %0, %1, %2" : "=v"(r) : "v"(lo), "v"(hi)); return r; }
;     __device__ __forceinline__ void operator()(const f32x4 (&acc)[2][2][4][2], const Unit& u, int wr, int wc, int fr, int fq) const {
;     ...
; #pragma unroll
;         for (int g = 0; g < 8; ++g) {
;             const int ai = g >> 2, m = g & 3;
;             bf16_t* rowp = O + (size_t)(row0 + ai * HALF + m * 16) * 8192 + col0;
; #pragma unroll
;             for (int bj = 0; bj < 2; ++bj) {
;                 const f32x4 v0 = acc[ai][bj][m][0], v1 = acc[ai][bj][m][1];
;                 f32x2 q[4];
; #pragma unroll
;                 for (int e = 0; e < 2; ++e) { float a0, a1, b0, b1;
;                     asm("v_max_f32 %0, 0, %1" : "=v"(a0) : "v"(v0[2 * e])); asm("v_max_f32 %0, 0, %1" : "=v"(a1) : "v"(v0[2 * e + 1]));
;                     asm("v_max_f32 %0, 0, %1" : "=v"(b0) : "v"(v1[2 * e])); asm("v_max_f32 %0, 0, %1" : "=v"(b1) : "v"(v1[2 * e + 1]));
;                     f32x2 pa = {a0, a1}, pb = {b0, b1};
;                     asm("v_pk_mul_f32 %0, %1, %1" : "=v"(q[e]) : "v"(pa)); asm("v_pk_mul_f32 %0, %1, %1" : "=v"(q[2 + e]) : "v"(pb)); }
;                 u32x4 w; w.x = cvt_pk_bf16(q[0][0], q[0][1]); w.y = cvt_pk_bf16(q[1][0], q[1][1]); w.z = cvt_pk_bf16(q[2][0], q[2][1]); w.w = cvt_pk_bf16(q[3][0], q[3][1]);
;                 *(u32x4*)(rowp + bj * HALF) = w;
;             }
;         }
.LBB0_823:
	v_lshl_add_u32 v144, s26, 8, v1
	v_lshl_or_b32 v146, s28, 8, v151
	v_ashrrev_i32_e32 v145, 31, v144
	v_ashrrev_i32_e32 v147, 31, v146
	v_lshlrev_b64 v[148:149], 14, v[144:145]
	v_max_f32 v122, 0, v122
	v_max_f32 v123, 0, v123
	v_lshl_add_u64 v[148:149], s[8:9], 0, v[148:149]
	v_lshlrev_b64 v[146:147], 1, v[146:147]
	v_max_f32 v126, 0, v126
	v_max_f32 v127, 0, v127
	v_pk_mul_f32 v[156:157], v[122:123], v[122:123]
	v_max_f32 v122, 0, v128
	v_max_f32 v123, 0, v129
	v_lshl_add_u64 v[148:149], v[148:149], 0, v[146:147]
	v_pk_mul_f32 v[126:127], v[126:127], v[126:127]
	v_max_f32 v124, 0, v124
	v_max_f32 v125, 0, v125
	v_pk_mul_f32 v[128:129], v[122:123], v[122:123]
	v_max_f32 v114, 0, v114
	v_max_f32 v118, 0, v118
	s_nop 0
	v_cvt_pk_bf16_f32 v122, v126, v127
	v_max_f32 v119, 0, v119
	v_pk_mul_f32 v[158:159], v[124:125], v[124:125]
	v_cvt_pk_bf16_f32 v123, v128, v129
	v_cvt_pk_bf16_f32 v124, v156, v157
	v_max_f32 v115, 0, v115
	v_max_f32 v116, 0, v116
	s_nop 0
	v_pk_mul_f32 v[118:119], v[118:119], v[118:119]
	v_cvt_pk_bf16_f32 v125, v158, v159
	global_store_dwordx4 v[148:149], v[122:125], off
	v_max_f32 v117, 0, v117
	v_max_f32 v106, 0, v106
	v_max_f32 v107, 0, v107
	v_max_f32 v110, 0, v110
	v_max_f32 v111, 0, v111
	s_nop 1
	v_pk_mul_f32 v[122:123], v[114:115], v[114:115]
	v_max_f32 v114, 0, v120
	v_max_f32 v115, 0, v121
	v_pk_mul_f32 v[124:125], v[116:117], v[116:117]
	v_max_f32 v108, 0, v108
	v_pk_mul_f32 v[110:111], v[110:111], v[110:111]
	v_max_f32 v109, 0, v109
	v_max_f32 v98, 0, v98
	s_nop 0
	v_pk_mul_f32 v[120:121], v[114:115], v[114:115]
	v_cvt_pk_bf16_f32 v114, v118, v119
	v_max_f32 v102, 0, v102
	v_max_f32 v103, 0, v103
	v_pk_mul_f32 v[118:119], v[108:109], v[108:109]
	v_max_f32 v99, 0, v99
	s_nop 0
	v_cvt_pk_bf16_f32 v115, v120, v121
	v_cvt_pk_bf16_f32 v116, v122, v123
	v_cvt_pk_bf16_f32 v117, v124, v125
	global_store_dwordx4 v[148:149], v[114:117], off offset:256
	v_pk_mul_f32 v[102:103], v[102:103], v[102:103]
	v_max_f32 v100, 0, v100
	v_max_f32 v101, 0, v101
	v_max_f32 v90, 0, v90
	v_max_f32 v91, 0, v91
	s_nop 1
	v_or_b32_e32 v114, 16, v144
	v_ashrrev_i32_e32 v115, 31, v114
	v_lshlrev_b64 v[114:115], 14, v[114:115]
	v_lshl_add_u64 v[114:115], s[8:9], 0, v[114:115]
	v_pk_mul_f32 v[116:117], v[106:107], v[106:107]
	v_max_f32 v106, 0, v112
	v_max_f32 v107, 0, v113
	v_lshl_add_u64 v[114:115], v[114:115], 0, v[146:147]
	v_pk_mul_f32 v[112:113], v[106:107], v[106:107]
	v_cvt_pk_bf16_f32 v106, v110, v111
	v_max_f32 v94, 0, v94
	v_max_f32 v95, 0, v95
	v_max_f32 v92, 0, v92
	v_max_f32 v93, 0, v93
	s_nop 0
	v_cvt_pk_bf16_f32 v107, v112, v113
	v_cvt_pk_bf16_f32 v108, v116, v117
	v_cvt_pk_bf16_f32 v109, v118, v119
	global_store_dwordx4 v[114:115], v[106:109], off
	v_pk_mul_f32 v[94:95], v[94:95], v[94:95]
	v_max_f32 v82, 0, v82
	v_max_f32 v86, 0, v86
	v_max_f32 v87, 0, v87
	v_max_f32 v83, 0, v83
	s_nop 1
	v_pk_mul_f32 v[106:107], v[98:99], v[98:99]
	v_max_f32 v98, 0, v104
	v_max_f32 v99, 0, v105
	v_pk_mul_f32 v[108:109], v[100:101], v[100:101]
	v_pk_mul_f32 v[86:87], v[86:87], v[86:87]
	v_max_f32 v84, 0, v84
	v_max_f32 v85, 0, v85
	v_max_f32 v74, 0, v74
	s_nop 0
	v_pk_mul_f32 v[104:105], v[98:99], v[98:99]
	v_cvt_pk_bf16_f32 v98, v102, v103
	v_pk_mul_f32 v[102:103], v[92:93], v[92:93]
	v_max_f32 v75, 0, v75
	v_max_f32 v78, 0, v78
	v_max_f32 v79, 0, v79
	s_nop 0
	v_cvt_pk_bf16_f32 v99, v104, v105
	v_cvt_pk_bf16_f32 v100, v106, v107
	v_cvt_pk_bf16_f32 v101, v108, v109
	global_store_dwordx4 v[114:115], v[98:101], off offset:256
	v_pk_mul_f32 v[78:79], v[78:79], v[78:79]
	v_max_f32 v76, 0, v76
	v_max_f32 v77, 0, v77
	v_max_f32 v66, 0, v66
	v_max_f32 v67, 0, v67
	s_nop 1
	v_or_b32_e32 v98, 32, v144
	v_ashrrev_i32_e32 v99, 31, v98
	v_lshlrev_b64 v[98:99], 14, v[98:99]
	v_lshl_add_u64 v[98:99], s[8:9], 0, v[98:99]
	v_pk_mul_f32 v[100:101], v[90:91], v[90:91]
	v_max_f32 v90, 0, v96
	v_max_f32 v91, 0, v97
	v_lshl_add_u64 v[98:99], v[98:99], 0, v[146:147]
	v_pk_mul_f32 v[96:97], v[90:91], v[90:91]
	v_cvt_pk_bf16_f32 v90, v94, v95
	v_max_f32 v70, 0, v70
	v_max_f32 v71, 0, v71
	v_max_f32 v68, 0, v68
	v_max_f32 v69, 0, v69
	s_nop 0
	v_cvt_pk_bf16_f32 v91, v96, v97
	v_cvt_pk_bf16_f32 v92, v100, v101
	v_cvt_pk_bf16_f32 v93, v102, v103
	global_store_dwordx4 v[98:99], v[90:93], off
	v_pk_mul_f32 v[70:71], v[70:71], v[70:71]
	v_max_f32 v62, 0, v62
	v_max_f32 v63, 0, v63
	v_max_f32 v58, 0, v58
	v_max_f32 v59, 0, v59
	s_nop 1
	v_pk_mul_f32 v[90:91], v[82:83], v[82:83]
	v_max_f32 v82, 0, v88
	v_max_f32 v83, 0, v89
	v_pk_mul_f32 v[92:93], v[84:85], v[84:85]
	v_pk_mul_f32 v[62:63], v[62:63], v[62:63]
	v_max_f32 v60, 0, v60
	v_max_f32 v61, 0, v61
	v_max_f32 v50, 0, v50
	s_nop 0
	v_pk_mul_f32 v[88:89], v[82:83], v[82:83]
	v_cvt_pk_bf16_f32 v82, v86, v87
	v_pk_mul_f32 v[86:87], v[76:77], v[76:77]
	v_max_f32 v54, 0, v54
	v_max_f32 v55, 0, v55
	v_max_f32 v51, 0, v51
	s_nop 0
	v_cvt_pk_bf16_f32 v83, v88, v89
	v_cvt_pk_bf16_f32 v84, v90, v91
	v_cvt_pk_bf16_f32 v85, v92, v93
	global_store_dwordx4 v[98:99], v[82:85], off offset:256
	v_pk_mul_f32 v[54:55], v[54:55], v[54:55]
	v_max_f32 v52, 0, v52
	v_max_f32 v53, 0, v53
	v_max_f32 v42, 0, v42
	v_max_f32 v43, 0, v43
	s_nop 1
	v_or_b32_e32 v82, 48, v144
	v_ashrrev_i32_e32 v83, 31, v82
	v_lshlrev_b64 v[82:83], 14, v[82:83]
	v_lshl_add_u64 v[82:83], s[8:9], 0, v[82:83]
	v_pk_mul_f32 v[84:85], v[74:75], v[74:75]
	v_max_f32 v74, 0, v80
	v_max_f32 v75, 0, v81
	v_lshl_add_u64 v[82:83], v[82:83], 0, v[146:147]
	v_pk_mul_f32 v[80:81], v[74:75], v[74:75]
	v_cvt_pk_bf16_f32 v74, v78, v79
	v_max_f32 v46, 0, v46
	v_max_f32 v47, 0, v47
	v_max_f32 v44, 0, v44
; __device__ __forceinline__ unsigned cvt_pk_bf16(float lo, float hi) { unsigned r; asm volatile("v_cvt_pk_bf16_f32 %0, %1, %2" : "=v"(r) : "v"(lo), "v"(hi)); return r; }
;     __device__ __forceinline__ void operator()(const f32x4 (&acc)[2][2][4][2], const Unit& u, int wr, int wc, int fr, int fq) const {
;     ...
; #pragma unroll
;         for (int g = 0; g < 8; ++g) {
;             const int ai = g >> 2, m = g & 3;
;             bf16_t* rowp = O + (size_t)(row0 + ai * HALF + m * 16) * 8192 + col0;
; #pragma unroll
;             for (int bj = 0; bj < 2; ++bj) {
;                 const f32x4 v0 = acc[ai][bj][m][0], v1 = acc[ai][bj][m][1];
;                 f32x2 q[4];
; #pragma unroll
;                 for (int e = 0; e < 2; ++e) { float a0, a1, b0, b1;
;                     asm("v_max_f32 %0, 0, %1" : "=v"(a0) : "v"(v0[2 * e])); asm("v_max_f32 %0, 0, %1" : "=v"(a1) : "v"(v0[2 * e + 1]));
;                     asm("v_max_f32 %0, 0, %1" : "=v"(b0) : "v"(v1[2 * e])); asm("v_max_f32 %0, 0, %1" : "=v"(b1) : "v"(v1[2 * e + 1]));
;                     f32x2 pa = {a0, a1}, pb = {b0, b1};
;                     asm("v_pk_mul_f32 %0, %1, %1" : "=v"(q[e]) : "v"(pa)); asm("v_pk_mul_f32 %0, %1, %1" : "=v"(q[2 + e]) : "v"(pb)); }
;                 u32x4 w; w.x = cvt_pk_bf16(q[0][0], q[0][1]); w.y = cvt_pk_bf16(q[1][0], q[1][1]); w.z = cvt_pk_bf16(q[2][0], q[2][1]); w.w = cvt_pk_bf16(q[3][0], q[3][1]);
;                 *(u32x4*)(rowp + bj * HALF) = w;
;             }
;         }
	v_max_f32 v45, 0, v45
	s_nop 0
	v_cvt_pk_bf16_f32 v75, v80, v81
	v_cvt_pk_bf16_f32 v76, v84, v85
	v_cvt_pk_bf16_f32 v77, v86, v87
	global_store_dwordx4 v[82:83], v[74:77], off
	v_pk_mul_f32 v[46:47], v[46:47], v[46:47]
	v_max_f32 v34, 0, v34
	v_max_f32 v38, 0, v38
	v_max_f32 v39, 0, v39
	v_max_f32 v35, 0, v35
	s_nop 1
	v_pk_mul_f32 v[74:75], v[66:67], v[66:67]
	v_max_f32 v66, 0, v72
	v_max_f32 v67, 0, v73
	v_pk_mul_f32 v[76:77], v[68:69], v[68:69]
	v_pk_mul_f32 v[38:39], v[38:39], v[38:39]
	v_max_f32 v36, 0, v36
	v_max_f32 v37, 0, v37
	v_max_f32 v26, 0, v26
	s_nop 0
	v_pk_mul_f32 v[72:73], v[66:67], v[66:67]
	v_cvt_pk_bf16_f32 v66, v70, v71
	v_pk_mul_f32 v[70:71], v[60:61], v[60:61]
	v_max_f32 v27, 0, v27
	v_max_f32 v30, 0, v30
	v_max_f32 v31, 0, v31
	s_nop 0
	v_cvt_pk_bf16_f32 v67, v72, v73
	v_cvt_pk_bf16_f32 v68, v74, v75
	v_cvt_pk_bf16_f32 v69, v76, v77
	global_store_dwordx4 v[82:83], v[66:69], off offset:256
	v_pk_mul_f32 v[30:31], v[30:31], v[30:31]
	v_max_f32 v28, 0, v28
	v_max_f32 v29, 0, v29
	v_max_f32 v18, 0, v18
	v_max_f32 v22, 0, v22
	s_nop 1
	v_pk_mul_f32 v[68:69], v[58:59], v[58:59]
	v_max_f32 v58, 0, v64
	v_max_f32 v59, 0, v65
	v_lshl_add_u64 v[66:67], v[148:149], 0, s[14:15]
	v_pk_mul_f32 v[64:65], v[58:59], v[58:59]
	v_cvt_pk_bf16_f32 v58, v62, v63
	v_add_co_u32_e32 v62, vcc, s50, v148
	v_cvt_pk_bf16_f32 v59, v64, v65
	v_cvt_pk_bf16_f32 v60, v68, v69
	v_cvt_pk_bf16_f32 v61, v70, v71
	v_max_f32 v23, 0, v23
	s_nop 1
	v_addc_co_u32_e32 v63, vcc, 0, v149, vcc
	global_store_dwordx4 v[62:63], v[58:61], off
	v_max_f32 v19, 0, v19
	v_pk_mul_f32 v[22:23], v[22:23], v[22:23]
	v_max_f32 v20, 0, v20
	v_max_f32 v21, 0, v21
	v_max_f32 v10, 0, v10
	s_nop 1
	v_pk_mul_f32 v[58:59], v[50:51], v[50:51]
	v_max_f32 v50, 0, v56
	v_max_f32 v51, 0, v57
	v_pk_mul_f32 v[60:61], v[52:53], v[52:53]
	v_max_f32 v11, 0, v11
	v_max_f32 v14, 0, v14
	v_max_f32 v15, 0, v15
	v_max_f32 v12, 0, v12
	s_nop 0
	v_pk_mul_f32 v[56:57], v[50:51], v[50:51]
	v_cvt_pk_bf16_f32 v50, v54, v55
	v_pk_mul_f32 v[54:55], v[44:45], v[44:45]
	v_max_f32 v13, 0, v13
	v_pk_mul_f32 v[14:15], v[14:15], v[14:15]
	v_max_f32 v2, 0, v2
	s_nop 0
	v_cvt_pk_bf16_f32 v51, v56, v57
	v_cvt_pk_bf16_f32 v52, v58, v59
	v_cvt_pk_bf16_f32 v53, v60, v61
	global_store_dwordx4 v[66:67], v[50:53], off offset:256
	v_max_f32 v3, 0, v3
	v_max_f32 v6, 0, v6
	v_max_f32 v7, 0, v7
	v_max_f32 v4, 0, v4
	v_max_f32 v5, 0, v5
	s_nop 1
	v_add_u32_e32 v50, 0x90, v144
	v_ashrrev_i32_e32 v51, 31, v50
	v_lshlrev_b64 v[50:51], 14, v[50:51]
	v_lshl_add_u64 v[50:51], s[8:9], 0, v[50:51]
	v_pk_mul_f32 v[52:53], v[42:43], v[42:43]
	v_max_f32 v42, 0, v48
	v_max_f32 v43, 0, v49
	v_lshl_add_u64 v[50:51], v[50:51], 0, v[146:147]
	v_pk_mul_f32 v[48:49], v[42:43], v[42:43]
	v_cvt_pk_bf16_f32 v42, v46, v47
	s_andn2_b64 vcc, exec, s[20:21]
	v_cvt_pk_bf16_f32 v43, v48, v49
	v_cvt_pk_bf16_f32 v44, v52, v53
	v_cvt_pk_bf16_f32 v45, v54, v55
	global_store_dwordx4 v[50:51], v[42:45], off
	s_mov_b64 s[20:21], -1
	v_pk_mul_f32 v[6:7], v[6:7], v[6:7]
	s_nop 0
	v_pk_mul_f32 v[42:43], v[34:35], v[34:35]
	v_max_f32 v34, 0, v40
	v_max_f32 v35, 0, v41
	v_pk_mul_f32 v[44:45], v[36:37], v[36:37]
	s_nop 0
	v_pk_mul_f32 v[40:41], v[34:35], v[34:35]
	v_cvt_pk_bf16_f32 v34, v38, v39
	v_pk_mul_f32 v[38:39], v[28:29], v[28:29]
	s_nop 0
	v_cvt_pk_bf16_f32 v35, v40, v41
	v_cvt_pk_bf16_f32 v36, v42, v43
	v_cvt_pk_bf16_f32 v37, v44, v45
	global_store_dwordx4 v[50:51], v[34:37], off offset:256
	s_nop 1
	v_add_u32_e32 v34, 0xa0, v144
	v_ashrrev_i32_e32 v35, 31, v34
	v_lshlrev_b64 v[34:35], 14, v[34:35]
	v_lshl_add_u64 v[34:35], s[8:9], 0, v[34:35]
	v_pk_mul_f32 v[36:37], v[26:27], v[26:27]
	v_max_f32 v26, 0, v32
	v_max_f32 v27, 0, v33
	v_lshl_add_u64 v[34:35], v[34:35], 0, v[146:147]
	v_pk_mul_f32 v[32:33], v[26:27], v[26:27]
	v_cvt_pk_bf16_f32 v26, v30, v31
	s_nop 0
	v_cvt_pk_bf16_f32 v27, v32, v33
	v_cvt_pk_bf16_f32 v28, v36, v37
	v_cvt_pk_bf16_f32 v29, v38, v39
	global_store_dwordx4 v[34:35], v[26:29], off
	s_nop 1
	v_pk_mul_f32 v[26:27], v[18:19], v[18:19]
	v_max_f32 v18, 0, v24
	v_max_f32 v19, 0, v25
	v_pk_mul_f32 v[28:29], v[20:21], v[20:21]
	s_nop 0
	v_pk_mul_f32 v[24:25], v[18:19], v[18:19]
	v_cvt_pk_bf16_f32 v18, v22, v23
	v_pk_mul_f32 v[22:23], v[12:13], v[12:13]
	s_nop 0
	v_cvt_pk_bf16_f32 v19, v24, v25
	v_cvt_pk_bf16_f32 v20, v26, v27
	v_cvt_pk_bf16_f32 v21, v28, v29
	global_store_dwordx4 v[34:35], v[18:21], off offset:256
	s_nop 1
	v_add_u32_e32 v18, 0xb0, v144
	v_ashrrev_i32_e32 v19, 31, v18
	v_lshlrev_b64 v[18:19], 14, v[18:19]
	v_lshl_add_u64 v[18:19], s[8:9], 0, v[18:19]
	v_pk_mul_f32 v[20:21], v[10:11], v[10:11]
	v_max_f32 v10, 0, v16
	v_max_f32 v11, 0, v17
	v_lshl_add_u64 v[18:19], v[18:19], 0, v[146:147]
	v_pk_mul_f32 v[16:17], v[10:11], v[10:11]
	v_cvt_pk_bf16_f32 v10, v14, v15
	s_nop 0
	v_cvt_pk_bf16_f32 v11, v16, v17
	v_cvt_pk_bf16_f32 v12, v20, v21
	v_cvt_pk_bf16_f32 v13, v22, v23
	global_store_dwordx4 v[18:19], v[10:13], off
	s_nop 1
	v_pk_mul_f32 v[10:11], v[2:3], v[2:3]
	v_max_f32 v2, 0, v8
	v_max_f32 v3, 0, v9
	v_pk_mul_f32 v[12:13], v[4:5], v[4:5]
	s_nop 0
	v_pk_mul_f32 v[8:9], v[2:3], v[2:3]
	v_cvt_pk_bf16_f32 v2, v6, v7
	s_nop 0
	v_cvt_pk_bf16_f32 v3, v8, v9
	v_cvt_pk_bf16_f32 v4, v10, v11
	v_cvt_pk_bf16_f32 v5, v12, v13
	global_store_dwordx4 v[18:19], v[2:5], off offset:256
	s_cbranch_vccnz .LBB0_795
	s_andn2_b64 vcc, exec, s[0:1]
	s_cbranch_vccnz .LBB0_794
	s_branch .LBB0_794
.LBB0_826:
	s_waitcnt vmcnt(0)
	s_and_b64 vcc, exec, s[12:13]
	s_cbranch_vccz .Lna4_x
	s_barrier
.Lna4_x:
	s_barrier
	s_cmp_lt_i32 s61, 6
	s_cbranch_scc1 .LBB0_928
